# k41: k40 + attention prologue scan waits exact on both wave paths (waves without Q rows issue four dummy loads)
# speedup vs baseline: 1.0077x; 1.0044x over previous
; #define ATT_GLD16(dst, ptr) asm volatile("global_load_dwordx4 %0, %1, off" : "=&v"(dst) : "v"(ptr) : "memory")
; __device__ __forceinline__ void attn_unit(const UnitDesc& u, LAS unsigned char* shm, float qkmax, float thresh) {
;     ...
;     { const int t2 = NT >= 2 ? NT - 2 : 0, t3 = NT >= 3 ? NT - 3 : 0, t4 = NT >= 4 ? NT - 4 : 0;
;       ATT_GLD16(kA, ksrc + (size_t)t2 * 64 * 512); ATT_GLD16(vA, vsrc + (size_t)t2 * 64 * 512);
;       ATT_GLD16(kB, ksrc + (size_t)t3 * 64 * 512); ATT_GLD16(vB, vsrc + (size_t)t3 * 64 * 512);
;       ATT_GLD16(kC, ksrc + (size_t)t4 * 64 * 512); ATT_GLD16(vC, vsrc + (size_t)t4 * 64 * 512); }
;     bf16x8 qr[4];
; #pragma unroll
;     for (int d0 = 0; d0 < 4; ++d0) qr[d0] = (bf16x8){0, 0, 0, 0, 0, 0, 0, 0};
;     if (active) { const bf16_t* Qw = u.Q + (size_t)(wid * 32 + r32) * 512;
; #pragma unroll
;         for (int d0 = 0; d0 < 4; ++d0) qr[d0] = *(const bf16x8*)(Qw + d0 * 16 + hi * 8); }
;     float carry = 0.f, Rown = 0.f, Rq0 = 0.f, inc4[4];
; #pragma unroll
;     for (int i = 0; i < 4; ++i) inc4[i] = suffix_incl(lfb[i], lane);
.LBB0_733:
	global_load_dword v190, v[20:21], off
	global_load_dword v190, v[20:21], off
	global_load_dword v190, v[20:21], off
	global_load_dword v190, v[20:21], off
	v_mov_b32_e32 v90, 0
	v_mov_b32_e32 v91, v90
	v_mov_b32_e32 v92, v90
	v_mov_b32_e32 v93, v90
	v_mov_b32_e32 v94, v90
	v_mov_b32_e32 v95, v90
	v_mov_b32_e32 v96, v90
	v_mov_b32_e32 v97, v90
	v_mov_b32_e32 v98, v90
	v_mov_b32_e32 v99, v90
	v_mov_b32_e32 v100, v90
	v_mov_b32_e32 v101, v90
	v_mov_b32_e32 v102, v90
	v_mov_b32_e32 v103, v90
	v_mov_b32_e32 v104, v90
	v_mov_b32_e32 v105, v90
.LBB0_734:
	s_lshl_b64 s[12:13], s[28:29], 16
	v_lshl_add_u64 v[188:189], v[106:107], 0, s[12:13]
	global_load_dwordx4 v[66:69], v[188:189], off
	v_lshl_add_u64 v[188:189], v[108:109], 0, s[12:13]
	global_load_dwordx4 v[74:77], v[188:189], off
	s_lshl_b64 s[8:9], s[8:9], 16
	v_lshl_add_u64 v[188:189], v[106:107], 0, s[8:9]
	global_load_dwordx4 v[70:73], v[188:189], off
	v_lshl_add_u64 v[188:189], v[108:109], 0, s[8:9]
	global_load_dwordx4 v[82:85], v[188:189], off
	s_lshl_b64 s[8:9], s[10:11], 16
	v_lshl_add_u64 v[188:189], v[106:107], 0, s[8:9]
	global_load_dwordx4 v[78:81], v[188:189], off
	v_lshl_add_u64 v[188:189], v[108:109], 0, s[8:9]
	global_load_dwordx4 v[86:89], v[188:189], off
	v_lshrrev_b32_e32 v0, 4, v137
	v_cmp_ne_u32_e64 s[8:9], 1, v0
	v_cmp_eq_u32_e64 s[10:11], 2, v0
	s_waitcnt vmcnt(13)
	v_add_f32_dpp v0, v14, v14 row_shl:1 row_mask:0xf bank_mask:0xf bound_ctrl:1
	v_cmp_lt_u32_e64 s[6:7], 15, v137
	s_nop 0
	v_add_f32_dpp v0, v0, v0 row_shl:2 row_mask:0xf bank_mask:0xf bound_ctrl:1
	s_nop 1
	v_add_f32_dpp v0, v0, v0 row_shl:4 row_mask:0xf bank_mask:0xf bound_ctrl:1
	s_nop 1
	v_add_f32_dpp v0, v0, v0 row_shl:8 row_mask:0xf bank_mask:0xf bound_ctrl:1
	s_nop 0
	v_readlane_b32 s28, v0, 16
	v_readlane_b32 s70, v0, 32
	v_readlane_b32 s69, v0, 48
	s_and_saveexec_b64 s[12:13], s[6:7]
	s_xor_b64 s[12:13], exec, s[12:13]
	s_cbranch_execz .LBB0_740
	s_and_saveexec_b64 s[64:65], s[8:9]
	s_xor_b64 s[64:65], exec, s[64:65]
	v_mov_b32_e32 v11, s69
	v_cndmask_b32_e64 v11, 0, v11, s[10:11]
	s_andn2_saveexec_b64 s[64:65], s[64:65]
	v_mov_b32_e32 v11, s69
	v_add_f32_e32 v11, s70, v11
	s_or_b64 exec, exec, s[64:65]
.LBB0_740:
	s_andn2_saveexec_b64 s[12:13], s[12:13]
	v_mov_b32_e32 v11, s70
	v_add_f32_e32 v11, s28, v11
	v_add_f32_e32 v11, s69, v11
	s_or_b64 exec, exec, s[12:13]
	s_waitcnt vmcnt(12)
	v_add_f32_dpp v15, v140, v140 row_shl:1 row_mask:0xf bank_mask:0xf bound_ctrl:1
	s_nop 1
	v_add_f32_dpp v15, v15, v15 row_shl:2 row_mask:0xf bank_mask:0xf bound_ctrl:1
	s_nop 1
	v_add_f32_dpp v15, v15, v15 row_shl:4 row_mask:0xf bank_mask:0xf bound_ctrl:1
	s_nop 1
	v_add_f32_dpp v15, v15, v15 row_shl:8 row_mask:0xf bank_mask:0xf bound_ctrl:1
	s_nop 0
	v_readlane_b32 s28, v15, 16
	v_readlane_b32 s70, v15, 32
	v_readlane_b32 s69, v15, 48
	s_and_saveexec_b64 s[12:13], s[6:7]
	s_xor_b64 s[12:13], exec, s[12:13]
	s_cbranch_execz .LBB0_748
	s_and_saveexec_b64 s[64:65], s[8:9]
	s_xor_b64 s[64:65], exec, s[64:65]
	v_mov_b32_e32 v16, s69
	v_cndmask_b32_e64 v16, 0, v16, s[10:11]
	s_andn2_saveexec_b64 s[64:65], s[64:65]
	v_mov_b32_e32 v16, s69
	v_add_f32_e32 v16, s70, v16
	s_or_b64 exec, exec, s[64:65]
.LBB0_748:
	s_andn2_saveexec_b64 s[12:13], s[12:13]
	v_mov_b32_e32 v16, s70
	v_add_f32_e32 v16, s28, v16
	v_add_f32_e32 v16, s69, v16
	s_or_b64 exec, exec, s[12:13]
	s_waitcnt vmcnt(11)
	v_add_f32_dpp v17, v141, v141 row_shl:1 row_mask:0xf bank_mask:0xf bound_ctrl:1
	s_nop 1
	v_add_f32_dpp v17, v17, v17 row_shl:2 row_mask:0xf bank_mask:0xf bound_ctrl:1
	s_nop 1
	v_add_f32_dpp v17, v17, v17 row_shl:4 row_mask:0xf bank_mask:0xf bound_ctrl:1
	s_nop 1
	v_add_f32_dpp v17, v17, v17 row_shl:8 row_mask:0xf bank_mask:0xf bound_ctrl:1
	s_nop 0
	v_readlane_b32 s28, v17, 16
	v_readlane_b32 s70, v17, 32
	v_readlane_b32 s69, v17, 48
	s_and_saveexec_b64 s[12:13], s[6:7]
	s_xor_b64 s[12:13], exec, s[12:13]
	s_cbranch_execz .LBB0_756
	s_and_saveexec_b64 s[64:65], s[8:9]
	s_xor_b64 s[64:65], exec, s[64:65]
	v_mov_b32_e32 v18, s69
	v_cndmask_b32_e64 v18, 0, v18, s[10:11]
	s_andn2_saveexec_b64 s[64:65], s[64:65]
	v_mov_b32_e32 v18, s69
	v_add_f32_e32 v18, s70, v18
	s_or_b64 exec, exec, s[64:65]
.LBB0_756:
	s_andn2_saveexec_b64 s[12:13], s[12:13]
	v_mov_b32_e32 v18, s70
	v_add_f32_e32 v18, s28, v18
	v_add_f32_e32 v18, s69, v18
	s_or_b64 exec, exec, s[12:13]
	s_waitcnt vmcnt(10)
	v_add_f32_dpp v19, v139, v139 row_shl:1 row_mask:0xf bank_mask:0xf bound_ctrl:1
	s_nop 1
	v_add_f32_dpp v19, v19, v19 row_shl:2 row_mask:0xf bank_mask:0xf bound_ctrl:1
	s_nop 1
	v_add_f32_dpp v19, v19, v19 row_shl:4 row_mask:0xf bank_mask:0xf bound_ctrl:1
	s_nop 1
	v_add_f32_dpp v19, v19, v19 row_shl:8 row_mask:0xf bank_mask:0xf bound_ctrl:1
	s_nop 0
	v_readlane_b32 s28, v19, 16
	v_readlane_b32 s70, v19, 32
	v_readlane_b32 s69, v19, 48
	s_and_saveexec_b64 s[12:13], s[6:7]
	s_xor_b64 s[12:13], exec, s[12:13]
	s_cbranch_execz .LBB0_764
	s_and_saveexec_b64 s[64:65], s[8:9]
	s_xor_b64 s[64:65], exec, s[64:65]
	v_mov_b32_e32 v20, s69
	v_cndmask_b32_e64 v20, 0, v20, s[10:11]
	s_andn2_saveexec_b64 s[64:65], s[64:65]
	v_mov_b32_e32 v20, s69
	v_add_f32_e32 v20, s70, v20
	s_or_b64 exec, exec, s[64:65]
